# ATTN k-loop: packed f32 mul/fma (O rescale, near-band bias add) unpacked into scalar v_mul/v_fma pairs
# speedup vs baseline: 1.0084x; 1.0084x over previous
.LBB0_1460:
	s_andn2_b64 vcc, exec, s[2:3]
	s_cbranch_vccnz .LBB0_1462
	v_lshl_add_u32 v252, v33, 2, s69
	v_add_u32_e32 v253, 0x80, v252
	ds_read2_b32 v[38:39], v253 offset0:32 offset1:31
	ds_read2_b32 v[36:37], v252 offset0:62 offset1:61
	ds_read2_b32 v[40:41], v252 offset0:56 offset1:55
	ds_read2_b32 v[34:35], v252 offset0:54 offset1:53
	ds_read2_b32 v[134:135], v252 offset0:48 offset1:47
	ds_read2_b32 v[44:45], v252 offset0:46 offset1:45
	ds_read2_b32 v[46:47], v252 offset0:40 offset1:39
	ds_read2_b32 v[42:43], v252 offset0:38 offset1:37
	s_waitcnt lgkmcnt(7)
	v_fma_f32 v38, v0, s44, v38
	v_fma_f32 v39, v1, s44, v39
	s_waitcnt lgkmcnt(6)
	v_fma_f32 v36, v2, s44, v36
	v_fma_f32 v37, v3, s44, v37
	v_max3_f32 v125, v38, s70, v39
	s_waitcnt lgkmcnt(5)
	v_fma_f32 v40, v4, s44, v40
	v_fma_f32 v41, v5, s44, v41
	v_max3_f32 v125, v125, v36, v37
	s_waitcnt lgkmcnt(4)
	v_fma_f32 v34, v6, s44, v34
	v_fma_f32 v35, v7, s44, v35
	v_max3_f32 v125, v125, v40, v41
	s_waitcnt lgkmcnt(3)
	v_fma_f32 v134, v8, s44, v134
	v_fma_f32 v135, v9, s44, v135
	v_max3_f32 v125, v125, v34, v35
	s_waitcnt lgkmcnt(2)
	v_fma_f32 v44, v10, s44, v44
	v_fma_f32 v45, v11, s44, v45
	v_max3_f32 v125, v125, v134, v135
	s_waitcnt lgkmcnt(1)
	v_fma_f32 v46, v12, s44, v46
	v_fma_f32 v47, v13, s44, v47
	v_max3_f32 v125, v125, v44, v45
	s_waitcnt lgkmcnt(0)
	v_fma_f32 v42, v14, s44, v42
	v_fma_f32 v43, v15, s44, v43
	v_max3_f32 v125, v125, v46, v47
	s_nop 0
	v_max3_f32 v125, v125, v42, v43
	ds_read2_b32 v[142:143], v252 offset0:32 offset1:31
	ds_read2_b32 v[138:139], v252 offset0:30 offset1:29
	ds_read2_b32 v[140:141], v252 offset0:24 offset1:23
	ds_read2_b32 v[136:137], v252 offset0:22 offset1:21
	ds_read2_b32 v[150:151], v252 offset0:16 offset1:15
	ds_read2_b32 v[146:147], v252 offset0:14 offset1:13
	ds_read2_b32 v[148:149], v252 offset0:8 offset1:7
	ds_read2_b32 v[144:145], v252 offset0:6 offset1:5
	s_waitcnt lgkmcnt(7)
	v_fma_f32 v142, v16, s44, v142
	v_fma_f32 v143, v17, s44, v143
	s_waitcnt lgkmcnt(6)
	v_fma_f32 v138, v18, s44, v138
	v_fma_f32 v139, v19, s44, v139
	v_max3_f32 v125, v125, v142, v143
	s_waitcnt lgkmcnt(5)
	v_fma_f32 v140, v20, s44, v140
	v_fma_f32 v141, v21, s44, v141
	v_max3_f32 v125, v125, v138, v139
	s_waitcnt lgkmcnt(4)
	v_fma_f32 v136, v22, s44, v136
	v_fma_f32 v137, v23, s44, v137
	v_max3_f32 v125, v125, v140, v141
	s_waitcnt lgkmcnt(3)
	v_fma_f32 v150, v24, s44, v150
	v_fma_f32 v151, v25, s44, v151
	v_max3_f32 v125, v125, v136, v137
	s_waitcnt lgkmcnt(2)
	v_fma_f32 v146, v26, s44, v146
	v_fma_f32 v147, v27, s44, v147
	v_max3_f32 v125, v125, v150, v151
	s_waitcnt lgkmcnt(1)
	v_fma_f32 v148, v28, s44, v148
	v_fma_f32 v149, v29, s44, v149
	v_max3_f32 v125, v125, v146, v147
	s_waitcnt lgkmcnt(0)
	v_fma_f32 v144, v30, s44, v144
	v_fma_f32 v145, v31, s44, v145
	v_max3_f32 v125, v125, v148, v149
	s_nop 0
	v_max3_f32 v129, v125, v144, v145

.LBB0_1465:
	v_lshrrev_b32_e32 v0, s40, v104
	v_and_b32_e32 v0, 1, v0
	v_cmp_eq_u32_e32 vcc, 1, v0
	s_or_b64 s[0:1], s[0:1], vcc
	v_cndmask_b32_e64 v0, v211, v129, s[0:1]
	ds_bpermute_b32 v1, v155, v0
	v_add_u32_e32 v252, s37, v204
	ds_read_b64_tr_b16 v[236:237], v252 offset:18432
	ds_read_b64_tr_b16 v[238:239], v252 offset:19584
	ds_read_b64_tr_b16 v[240:241], v252 offset:18496
	ds_read_b64_tr_b16 v[242:243], v252 offset:19648
	ds_read_b64_tr_b16 v[244:245], v252 offset:20736
	ds_read_b64_tr_b16 v[246:247], v252 offset:21888
	ds_read_b64_tr_b16 v[248:249], v252 offset:20800
	ds_read_b64_tr_b16 v[250:251], v252 offset:21952
	s_mov_b64 s[2:3], -1
	s_waitcnt lgkmcnt(8)
	v_max3_f32 v33, v123, v0, v1
	v_cmp_neq_f32_e32 vcc, s70, v33
	s_nop 1
	v_cndmask_b32_e32 v125, 0, v33, vcc
	v_cndmask_b32_e64 v253, v212, v125, s[0:1]
	v_sub_f32_e32 v0, v38, v253
	v_sub_f32_e32 v1, v39, v253
	v_sub_f32_e32 v2, v36, v253
	v_sub_f32_e32 v3, v37, v253
	v_sub_f32_e32 v4, v40, v253
	v_sub_f32_e32 v5, v41, v253
	v_sub_f32_e32 v6, v34, v253
	v_sub_f32_e32 v7, v35, v253
	v_sub_f32_e32 v8, v134, v253
	v_sub_f32_e32 v9, v135, v253
	v_sub_f32_e32 v10, v44, v253
	v_sub_f32_e32 v11, v45, v253
	v_sub_f32_e32 v12, v46, v253
	v_sub_f32_e32 v13, v47, v253
	v_sub_f32_e32 v14, v42, v253
	v_sub_f32_e32 v15, v43, v253
	v_sub_f32_e32 v16, v142, v253
	v_sub_f32_e32 v17, v143, v253
	v_sub_f32_e32 v18, v138, v253
	v_sub_f32_e32 v19, v139, v253
	v_sub_f32_e32 v20, v140, v253
	v_sub_f32_e32 v21, v141, v253
	v_sub_f32_e32 v22, v136, v253
	v_sub_f32_e32 v23, v137, v253
	v_sub_f32_e32 v24, v150, v253
	v_sub_f32_e32 v25, v151, v253
	v_sub_f32_e32 v26, v146, v253
	v_sub_f32_e32 v27, v147, v253
	v_sub_f32_e32 v28, v148, v253
	v_sub_f32_e32 v29, v149, v253
	v_sub_f32_e32 v30, v144, v253
	v_sub_f32_e32 v31, v145, v253
	v_sub_f32_e32 v34, v123, v125
	v_exp_f32_e32 v34, v34
	s_waitcnt lgkmcnt(6)
	ds_read_b64_tr_b16 v[134:135], v252 offset:23040
	ds_read_b64_tr_b16 v[136:137], v252 offset:24192
	ds_read_b64_tr_b16 v[138:139], v252 offset:23104
	ds_read_b64_tr_b16 v[140:141], v252 offset:24256
	ds_read_b64_tr_b16 v[142:143], v252 offset:25344
	ds_read_b64_tr_b16 v[144:145], v252 offset:26496
	ds_read_b64_tr_b16 v[146:147], v252 offset:25408
	ds_read_b64_tr_b16 v[148:149], v252 offset:26560
	v_cmp_neq_f32_e32 vcc, 1.0, v34
	v_mov_b32_e32 v37, 0
	s_cbranch_vccz .Lfa_norescale2
	v_mul_f32_e32 v78, v34, v78
	v_mul_f32_e32 v79, v34, v79
	v_mul_f32_e32 v76, v34, v76
	v_mul_f32_e32 v77, v34, v77
	v_mul_f32_e32 v74, v34, v74
	v_mul_f32_e32 v75, v34, v75
	v_mul_f32_e32 v72, v34, v72
	v_mul_f32_e32 v73, v34, v73
	v_mul_f32_e32 v70, v34, v70
	v_mul_f32_e32 v71, v34, v71
	v_mul_f32_e32 v68, v34, v68
	v_mul_f32_e32 v69, v34, v69
	v_mul_f32_e32 v66, v34, v66
	v_mul_f32_e32 v67, v34, v67
	v_mul_f32_e32 v64, v34, v64
	v_mul_f32_e32 v65, v34, v65
	v_mul_f32_e32 v62, v34, v62
	v_mul_f32_e32 v63, v34, v63
	v_mul_f32_e32 v60, v34, v60
	v_mul_f32_e32 v61, v34, v61
	v_mul_f32_e32 v58, v34, v58
	v_mul_f32_e32 v59, v34, v59
	v_mul_f32_e32 v56, v34, v56
	v_mul_f32_e32 v57, v34, v57
	v_mul_f32_e32 v54, v34, v54
	v_mul_f32_e32 v55, v34, v55
	v_mul_f32_e32 v52, v34, v52
	v_mul_f32_e32 v53, v34, v53
	v_mul_f32_e32 v50, v34, v50
	v_mul_f32_e32 v51, v34, v51
	v_mul_f32_e32 v48, v34, v48
	v_mul_f32_e32 v49, v34, v49

.Lfa_fast:
	v_mov_b32_e32 v33, s69
	ds_read_b32 v127, v33 offset:764
	v_max_f32_e32 v252, v0, v1
	v_max3_f32 v252, v252, v2, v3
	v_max3_f32 v252, v252, v4, v5
	v_max3_f32 v252, v252, v6, v7
	v_max3_f32 v252, v252, v8, v9
	v_max3_f32 v252, v252, v10, v11
	v_max3_f32 v252, v252, v12, v13
	v_max3_f32 v252, v252, v14, v15
	v_max3_f32 v252, v252, v16, v17
	v_max3_f32 v252, v252, v18, v19
	v_max3_f32 v252, v252, v20, v21
	v_max3_f32 v252, v252, v22, v23
	v_max3_f32 v252, v252, v24, v25
	v_max3_f32 v252, v252, v26, v27
	v_max3_f32 v252, v252, v28, v29
	v_max3_f32 v252, v252, v30, v31
	v_lshrrev_b32_e32 v253, s40, v104
	v_and_b32_e32 v253, 1, v253
	v_cmp_eq_u32_e32 vcc, 1, v253
	s_or_b64 s[0:1], s[0:1], vcc
	s_waitcnt lgkmcnt(0)
	v_fmamk_f32 v129, v252, 0x3fb8aa3b, v127
	v_cndmask_b32_e64 v252, v211, v129, s[0:1]
	ds_bpermute_b32 v253, v155, v252
	v_add_u32_e32 v47, s37, v204
	ds_read_b64_tr_b16 v[134:135], v47 offset:18432
	ds_read_b64_tr_b16 v[136:137], v47 offset:19584
	ds_read_b64_tr_b16 v[138:139], v47 offset:18496
	ds_read_b64_tr_b16 v[140:141], v47 offset:19648
	ds_read_b64_tr_b16 v[142:143], v47 offset:20736
	ds_read_b64_tr_b16 v[144:145], v47 offset:21888
	ds_read_b64_tr_b16 v[146:147], v47 offset:20800
	ds_read_b64_tr_b16 v[148:149], v47 offset:21952
	s_waitcnt lgkmcnt(8)
	v_max3_f32 v33, v123, v252, v253
	v_cmp_neq_f32_e32 vcc, s70, v33
	s_nop 1
	v_cndmask_b32_e32 v125, 0, v33, vcc
	v_sub_f32_e32 v252, v127, v125
	v_cndmask_b32_e64 v36, v211, v252, s[0:1]
	v_sub_f32_e32 v34, v123, v125
	v_exp_f32_e32 v34, v34
	s_waitcnt lgkmcnt(6)
	ds_read_b64_tr_b16 v[236:237], v47 offset:23040
	ds_read_b64_tr_b16 v[238:239], v47 offset:24192
	ds_read_b64_tr_b16 v[240:241], v47 offset:23104
	ds_read_b64_tr_b16 v[242:243], v47 offset:24256
	ds_read_b64_tr_b16 v[244:245], v47 offset:25344
	ds_read_b64_tr_b16 v[246:247], v47 offset:26496
	ds_read_b64_tr_b16 v[248:249], v47 offset:25408
	ds_read_b64_tr_b16 v[250:251], v47 offset:26560
	v_cmp_neq_f32_e32 vcc, 1.0, v34
	v_mov_b32_e32 v37, 0
	s_cbranch_vccz .Lfa_norescale
	v_mul_f32_e32 v78, v34, v78
	v_mul_f32_e32 v79, v34, v79
	v_mul_f32_e32 v76, v34, v76
	v_mul_f32_e32 v77, v34, v77
	v_mul_f32_e32 v74, v34, v74
	v_mul_f32_e32 v75, v34, v75
	v_mul_f32_e32 v72, v34, v72
	v_mul_f32_e32 v73, v34, v73
	v_mul_f32_e32 v70, v34, v70
	v_mul_f32_e32 v71, v34, v71
	v_mul_f32_e32 v68, v34, v68
	v_mul_f32_e32 v69, v34, v69
	v_mul_f32_e32 v66, v34, v66
	v_mul_f32_e32 v67, v34, v67
	v_mul_f32_e32 v64, v34, v64
	v_mul_f32_e32 v65, v34, v65
	v_mul_f32_e32 v62, v34, v62
	v_mul_f32_e32 v63, v34, v63
	v_mul_f32_e32 v60, v34, v60
	v_mul_f32_e32 v61, v34, v61
	v_mul_f32_e32 v58, v34, v58
	v_mul_f32_e32 v59, v34, v59
	v_mul_f32_e32 v56, v34, v56
	v_mul_f32_e32 v57, v34, v57
	v_mul_f32_e32 v54, v34, v54
	v_mul_f32_e32 v55, v34, v55
	v_mul_f32_e32 v52, v34, v52
	v_mul_f32_e32 v53, v34, v53
	v_mul_f32_e32 v50, v34, v50
	v_mul_f32_e32 v51, v34, v51
	v_mul_f32_e32 v48, v34, v48
	v_mul_f32_e32 v49, v34, v49
